# FFN-up unit loop: trailing wave-half runs the next-unit header and accumulator zeroing BEFORE its stagger barrier instead of after it (same barrier count and order)
# speedup vs baseline: 1.0067x; 1.0067x over previous
; #define PG8_STAGE(bufoff, gbase, voff) do { _Pragma("unroll") for (int _i = 0; _i < 2; ++_i) { \
;         const unsigned _m0 = ldsu + (unsigned)(bufoff) + ldsw + (unsigned)(_i * 8192); \
;         asm volatile("s_mov_b32 m0, %2\n\ts_nop 0\n\tglobal_load_lds_dwordx4 %0, %1" :: "v"((voff)[_i]), "s"((const char*)(gbase)), "s"(_m0) : "memory"); } } while (0)
; #define PG8_WAIT_V(n) asm volatile("s_waitcnt vmcnt(" #n ")" ::: "memory")
; #define PG8_BAR __builtin_amdgcn_s_barrier()
; template <class Epi>
; __device__ __forceinline__ void gemm_phase(LAS unsigned char* lds, const Gemm g, const StaticOrder& S, const Epi& E) {
;     ...
;     const char* cA = (const char*)g.A + (size_t)cur.pm * tstepA; const char* cB = (const char*)g.Bt + (size_t)cur.pn * tstepB;
;     PG8_STAGE(PG8_SB(0, 0), cB, voffB); PG8_STAGE(PG8_SA(0, 0), cA, voffA); PG8_STAGE(PG8_SA(0, 1), cA + hstepA, voffA); PG8_STAGE(PG8_SB(0, 1), cB + hstepB, voffB);
;     if (wr == 1) PG8_BAR;
;     PG8_WAIT_V(2); PG8_BAR;
;     PG8_STAGE(PG8_SB(1, 0), cB + kstep, voffB); PG8_STAGE(PG8_SA(1, 0), cA + kstep, voffA); PG8_STAGE(PG8_SA(1, 1), cA + hstepA + kstep, voffA);
;     PG8_WAIT_V(6); PG8_BAR;
;     for (;;) {
.LBB0_1021:
	s_lshl_b32 s86, s9, 6
	s_lshl_b32 s5, s9, 13
	s_lshl_b32 s87, s6, 5
	s_add_i32 s88, s47, 0x18000
	s_add_u32 s14, s10, 0x80
	s_waitcnt vmcnt(2)
	s_barrier
	s_addc_u32 s15, s11, 0
	s_mov_b32 m0, s88
	s_nop 0
	global_load_lds_dwordx4 v217, s[14:15]
	s_add_i32 s89, s47, 0x1a000
	s_mov_b32 m0, s89
	s_nop 0
	global_load_lds_dwordx4 v219, s[14:15]
	v_readlane_b32 s14, v254, 27
	s_add_i32 s95, s47, 0x8000
	v_readlane_b32 s15, v254, 28
	s_mov_b32 m0, s95
	s_nop 0
	global_load_lds_dwordx4 v216, s[14:15]
	s_add_i32 s37, s47, 0xa000
	s_add_i32 s56, s47, 0xc000
	s_add_i32 s57, s47, 0xe000
	s_add_i32 s58, s47, 0x1c000
	v_lshlrev_b32_e32 v5, 2, v214
	s_mov_b32 m0, s37
	s_nop 0
	global_load_lds_dwordx4 v218, s[14:15]
	v_readlane_b32 s14, v254, 31
	s_cmpk_lt_u32 s4, 0x100
	v_and_b32_e32 v5, 32, v5
	v_readlane_b32 s15, v254, 32
	s_mov_b32 m0, s56
	s_nop 0
	global_load_lds_dwordx4 v216, s[14:15]
	s_cselect_b64 s[90:91], -1, 0
	s_cmpk_gt_u32 s4, 0xff
	v_bitop3_b32 v4, v4, s5, v5 bitop3:0xde
	s_mov_b32 m0, s57
	s_nop 0
	global_load_lds_dwordx4 v218, s[14:15]
	s_cselect_b64 s[4:5], -1, 0
	s_lshl_b32 s59, s6, 6
	s_lshl_b32 s14, s9, 4
	s_lshl_b32 s15, s6, 2
	s_or_b32 s13, s13, s6
	s_or_b32 s6, s7, s6
	s_lshl_b32 s7, s9, 8
	v_readlane_b32 s9, v254, 58
	s_add_i32 s61, s9, s7
	s_lshl_b32 s7, s8, 2
	s_waitcnt vmcnt(6)
	s_lshl_b32 s13, s13, 9
	s_add_i32 s64, s9, s7
	v_readlane_b32 s7, v252, 33
	s_or_b32 s66, s15, s14
	s_lshl_b32 s6, s6, 9
	s_add_i32 s63, s7, s13
	s_add_i32 s62, s64, s12
	v_readlane_b32 s12, v254, 29
	s_add_i32 s60, s47, 0x1e000
	s_add_i32 s65, s7, s6
	s_add_i32 s66, s66, 0x1ffffe4
	v_add_u32_e32 v220, 0, v1
	v_add_u32_e32 v221, 0, v4
	v_add_u32_e32 v222, 0, v0
	v_add_u32_e32 v223, 0, v2
	v_add_u32_e32 v224, 0, v3
	v_readlane_b32 s67, v253, 52
	v_readlane_b32 s96, v254, 23
	v_readlane_b32 s13, v254, 30
	s_barrier
	v_readlane_b32 s97, v254, 24
	s_mov_b32 s32, 0
	s_branch .LBB0_1024

; #define PG8_STAGE(bufoff, gbase, voff) do { _Pragma("unroll") for (int _i = 0; _i < 2; ++_i) { \
;         const unsigned _m0 = ldsu + (unsigned)(bufoff) + ldsw + (unsigned)(_i * 8192); \
;         asm volatile("s_mov_b32 m0, %2\n\ts_nop 0\n\tglobal_load_lds_dwordx4 %0, %1" :: "v"((voff)[_i]), "s"((const char*)(gbase)), "s"(_m0) : "memory"); } } while (0)
; #define PG8_LDA(dst, b, h) do { _Pragma("unroll") for (int m = 0; m < 4; ++m) _Pragma("unroll") for (int k = 0; k < 2; ++k) dst[m][k] = *(const LAS bf16x8*)(lds + PG8_SA(b, h) + aoff + m * 2048 + k * 1024); } while (0)
; #define PG8_LDB(dst, b, h) do { _Pragma("unroll") for (int n = 0; n < 2; ++n) _Pragma("unroll") for (int k = 0; k < 2; ++k) dst[n][k] = *(const LAS bf16x8*)(lds + bbase[b][h] + n * 2048 + k * 1024); } while (0)
; #define PG8_WAIT_V(n) asm volatile("s_waitcnt vmcnt(" #n ")" ::: "memory")
; #define PG8_WAIT_L(n) asm volatile("s_waitcnt lgkmcnt(" #n ")" ::: "memory")
; #define PG8_BAR __builtin_amdgcn_s_barrier()
; #define PG8_SCHED __builtin_amdgcn_sched_barrier(0)
; template <class Epi>
; __device__ __forceinline__ void gemm_phase(LAS unsigned char* lds, const Gemm g, const StaticOrder& S, const Epi& E) {
;     ...
;         const bool has_next = S.next(ui + 1, nxt);
;         const char* nA = has_next ? (const char*)g.A + (size_t)nxt.pm * tstepA : cA; const char* nB = has_next ? (const char*)g.Bt + (size_t)nxt.pn * tstepB : cB;
;         for (int t = 0; t < nt; t += 2) {
;             const bool last = (t == nt - 2);
;             const char* a2 = last ? nA : cA + (size_t)(t + 2) * kstep; const char* b2 = last ? nB : cB + (size_t)(t + 2) * kstep;
;             const char* a3 = a2 + kstep; const char* b3 = b2 + kstep;
;             const char* b1 = cB + (size_t)(t + 1) * kstep;
;             PG8_LDB(B0, 0, 0); PG8_SCHED; PG8_LDA(At, 0, 0); PG8_LDA(At2, 0, 1); PG8_STAGE(PG8_SB(1, 1), b1 + hstepB, voffB);
;             PG8_WAIT_V(8); PG8_WAIT_L(0); PG8_BAR; PG8_MMA2B(0, At, At2, B0); PG8_BAR; PG8_SCHED;
;     ...
; #pragma unroll
;         for (int a = 0; a < 2; ++a)
; #pragma unroll
;             for (int b = 0; b < 2; ++b)
; #pragma unroll
;                 for (int m = 0; m < 4; ++m)
; #pragma unroll
;                     for (int n = 0; n < 2; ++n) acc[a][b][m][n] = (f32x4){0.f, 0.f, 0.f, 0.f};
;         cur = nxt; cA = nA; cB = nB; ++ui;
;         if (wr == 1) PG8_BAR;
.LBB0_1026:
	s_ashr_i32 s7, s6, 31
	s_lshl_b64 s[14:15], s[6:7], 19
	s_add_u32 s80, s22, s14
	s_addc_u32 s81, s23, s15
	s_and_b64 s[14:15], s[8:9], exec
	s_cselect_b32 s7, s81, s13
	s_cselect_b32 s97, s80, s12
	s_ashr_i32 s39, s38, 31
	s_lshl_b64 s[14:15], s[38:39], 19
	s_add_u32 s82, s28, s14
	s_addc_u32 s83, s29, s15
	s_and_b64 s[14:15], s[8:9], exec
	s_cselect_b32 s39, s83, s11
	s_cselect_b32 vcc_lo, s82, s10
	s_add_u32 vcc_hi, s12, 0x100
	v_mov_b32_e32 v0, 0
	s_addc_u32 s68, s13, 0
	s_mov_b32 s69, -2
	v_mov_b32_e32 v1, v0
	v_mov_b64_e32 v[2:3], 0
	v_mov_b64_e32 v[60:61], 0
	v_mov_b64_e32 v[62:63], 0
	v_mov_b64_e32 v[8:9], 0
	v_mov_b64_e32 v[10:11], 0
	v_mov_b64_e32 v[104:105], 0
	v_mov_b64_e32 v[106:107], 0
	v_mov_b64_e32 v[12:13], 0
	v_mov_b64_e32 v[14:15], 0
	v_mov_b64_e32 v[108:109], 0
	v_mov_b64_e32 v[110:111], 0
	v_mov_b64_e32 v[20:21], 0
	v_mov_b64_e32 v[22:23], 0
	v_mov_b64_e32 v[116:117], 0
	v_mov_b64_e32 v[118:119], 0
	v_mov_b64_e32 v[4:5], 0
	v_mov_b64_e32 v[6:7], 0
	v_mov_b64_e32 v[64:65], 0
	v_mov_b64_e32 v[66:67], 0
	v_mov_b64_e32 v[16:17], 0
	v_mov_b64_e32 v[18:19], 0
	v_mov_b64_e32 v[112:113], 0
	v_mov_b64_e32 v[114:115], 0
	v_mov_b64_e32 v[24:25], 0
	v_mov_b64_e32 v[26:27], 0
	v_mov_b64_e32 v[120:121], 0
	v_mov_b64_e32 v[122:123], 0
	v_mov_b64_e32 v[28:29], 0
	v_mov_b64_e32 v[30:31], 0
	v_mov_b64_e32 v[124:125], 0
	v_mov_b64_e32 v[126:127], 0
	v_mov_b64_e32 v[32:33], 0
	v_mov_b64_e32 v[34:35], 0
	v_mov_b64_e32 v[128:129], 0
	v_mov_b64_e32 v[130:131], 0
	v_mov_b64_e32 v[36:37], 0
	v_mov_b64_e32 v[38:39], 0
	v_mov_b64_e32 v[132:133], 0
	v_mov_b64_e32 v[134:135], 0
	v_mov_b64_e32 v[44:45], 0
	v_mov_b64_e32 v[46:47], 0
	v_mov_b64_e32 v[140:141], 0
	v_mov_b64_e32 v[142:143], 0
	v_mov_b64_e32 v[56:57], 0
	v_mov_b64_e32 v[58:59], 0
	v_mov_b64_e32 v[72:73], 0
	v_mov_b64_e32 v[74:75], 0
	v_mov_b64_e32 v[40:41], 0
	v_mov_b64_e32 v[42:43], 0
	v_mov_b64_e32 v[136:137], 0
	v_mov_b64_e32 v[138:139], 0
	v_mov_b64_e32 v[48:49], 0
	v_mov_b64_e32 v[50:51], 0
	v_mov_b64_e32 v[144:145], 0
	v_mov_b64_e32 v[146:147], 0
	v_mov_b64_e32 v[52:53], 0
	v_mov_b64_e32 v[54:55], 0
	v_mov_b64_e32 v[148:149], 0
	v_mov_b64_e32 v[150:151], 0
	v_mov_b64_e32 v[76:77], 0
	v_mov_b64_e32 v[78:79], 0
	v_mov_b64_e32 v[80:81], 0
	v_mov_b64_e32 v[82:83], 0
	s_cmp_eq_u32 s32, 1
	s_cbranch_scc0 .Lstag_skip
	s_barrier
.Lstag_skip:
.LBB0_1027:
	ds_read_b128 v[68:71], v220
	ds_read_b128 v[84:87], v220 offset:1024
	ds_read_b128 v[88:91], v220 offset:2048
	ds_read_b128 v[92:95], v220 offset:3072
	s_add_u32 s12, s10, 0x100
	s_addc_u32 s13, s11, 0
	s_cmp_eq_u32 s69, 12
	s_cselect_b32 s14, s97, vcc_hi
	s_cselect_b32 s15, s7, s68
	s_cselect_b32 s84, vcc_lo, s12
	s_cselect_b32 s85, s39, s13
	s_add_u32 s16, s14, 0x80
	s_addc_u32 s17, s15, 0
	ds_read_b128 v[96:99], v221
	ds_read_b128 v[100:103], v221 offset:1024
	ds_read_b128 v[152:155], v221 offset:2048
	ds_read_b128 v[156:159], v221 offset:3072
	ds_read_b128 v[166:169], v221 offset:4096
	ds_read_b128 v[178:181], v221 offset:5120
	ds_read_b128 v[182:185], v221 offset:6144
	ds_read_b128 v[186:189], v221 offset:7168
	ds_read_b128 v[190:193], v221 offset:16384
	ds_read_b128 v[194:197], v221 offset:17408
	ds_read_b128 v[198:201], v221 offset:18432
	ds_read_b128 v[202:205], v221 offset:19456
	ds_read_b128 v[226:229], v221 offset:20480
	ds_read_b128 v[230:233], v221 offset:21504
	ds_read_b128 v[234:237], v221 offset:22528
	ds_read_b128 v[238:241], v221 offset:23552
	s_add_u32 s10, s10, 0x40080
	s_addc_u32 s11, s11, 0
	s_mov_b32 m0, s58
	s_nop 0
	global_load_lds_dwordx4 v217, s[10:11]
	s_mov_b32 m0, s60
	s_nop 0
	global_load_lds_dwordx4 v219, s[10:11]
	s_waitcnt vmcnt(8)
	s_waitcnt lgkmcnt(0)
	s_barrier
	v_mfma_f32_16x16x32_bf16 v[80:83], v[68:71], v[96:99], v[80:83]
	v_mfma_f32_16x16x32_bf16 v[76:79], v[88:91], v[96:99], v[76:79]
	v_mfma_f32_16x16x32_bf16 v[148:151], v[68:71], v[152:155], v[148:151]
	v_mfma_f32_16x16x32_bf16 v[52:55], v[88:91], v[152:155], v[52:55]
	v_mfma_f32_16x16x32_bf16 v[144:147], v[68:71], v[166:169], v[144:147]
	v_mfma_f32_16x16x32_bf16 v[48:51], v[88:91], v[166:169], v[48:51]
	v_mfma_f32_16x16x32_bf16 v[136:139], v[68:71], v[182:185], v[136:139]
	v_mfma_f32_16x16x32_bf16 v[40:43], v[88:91], v[182:185], v[40:43]
	v_mfma_f32_16x16x32_bf16 v[124:127], v[68:71], v[190:193], v[124:127]
	v_mfma_f32_16x16x32_bf16 v[28:31], v[88:91], v[190:193], v[28:31]
	v_mfma_f32_16x16x32_bf16 v[120:123], v[68:71], v[198:201], v[120:123]
	v_mfma_f32_16x16x32_bf16 v[24:27], v[88:91], v[198:201], v[24:27]
	v_mfma_f32_16x16x32_bf16 v[112:115], v[68:71], v[226:229], v[112:115]
	v_mfma_f32_16x16x32_bf16 v[16:19], v[88:91], v[226:229], v[16:19]
	v_mfma_f32_16x16x32_bf16 v[64:67], v[68:71], v[234:237], v[64:67]
	v_mfma_f32_16x16x32_bf16 v[4:7], v[88:91], v[234:237], v[4:7]
	v_mfma_f32_16x16x32_bf16 v[80:83], v[84:87], v[100:103], v[80:83]
	v_mfma_f32_16x16x32_bf16 v[76:79], v[92:95], v[100:103], v[76:79]
	v_mfma_f32_16x16x32_bf16 v[148:151], v[84:87], v[156:159], v[148:151]
	v_mfma_f32_16x16x32_bf16 v[52:55], v[92:95], v[156:159], v[52:55]
	v_mfma_f32_16x16x32_bf16 v[144:147], v[84:87], v[178:181], v[144:147]
	v_mfma_f32_16x16x32_bf16 v[48:51], v[92:95], v[178:181], v[48:51]
	v_mfma_f32_16x16x32_bf16 v[136:139], v[84:87], v[186:189], v[136:139]
	v_mfma_f32_16x16x32_bf16 v[40:43], v[92:95], v[186:189], v[40:43]
	v_mfma_f32_16x16x32_bf16 v[124:127], v[84:87], v[194:197], v[124:127]
	v_mfma_f32_16x16x32_bf16 v[28:31], v[92:95], v[194:197], v[28:31]
	v_mfma_f32_16x16x32_bf16 v[120:123], v[84:87], v[202:205], v[120:123]
	v_mfma_f32_16x16x32_bf16 v[24:27], v[92:95], v[202:205], v[24:27]
	v_mfma_f32_16x16x32_bf16 v[112:115], v[84:87], v[230:233], v[112:115]
	v_mfma_f32_16x16x32_bf16 v[16:19], v[92:95], v[230:233], v[16:19]
	v_mfma_f32_16x16x32_bf16 v[64:67], v[84:87], v[238:241], v[64:67]
	v_mfma_f32_16x16x32_bf16 v[4:7], v[92:95], v[238:241], v[4:7]
	s_barrier
; #define PG8_STAGE(bufoff, gbase, voff) do { _Pragma("unroll") for (int _i = 0; _i < 2; ++_i) { \
;         const unsigned _m0 = ldsu + (unsigned)(bufoff) + ldsw + (unsigned)(_i * 8192); \
;         asm volatile("s_mov_b32 m0, %2\n\ts_nop 0\n\tglobal_load_lds_dwordx4 %0, %1" :: "v"((voff)[_i]), "s"((const char*)(gbase)), "s"(_m0) : "memory"); } } while (0)
; #define PG8_LDA(dst, b, h) do { _Pragma("unroll") for (int m = 0; m < 4; ++m) _Pragma("unroll") for (int k = 0; k < 2; ++k) dst[m][k] = *(const LAS bf16x8*)(lds + PG8_SA(b, h) + aoff + m * 2048 + k * 1024); } while (0)
; #define PG8_LDB(dst, b, h) do { _Pragma("unroll") for (int n = 0; n < 2; ++n) _Pragma("unroll") for (int k = 0; k < 2; ++k) dst[n][k] = *(const LAS bf16x8*)(lds + bbase[b][h] + n * 2048 + k * 1024); } while (0)
; #define PG8_WAIT_V(n) asm volatile("s_waitcnt vmcnt(" #n ")" ::: "memory")
; #define PG8_WAIT_L(n) asm volatile("s_waitcnt lgkmcnt(" #n ")" ::: "memory")
; #define PG8_BAR __builtin_amdgcn_s_barrier()
; #define PG8_SCHED __builtin_amdgcn_sched_barrier(0)
; template <class Epi>
; __device__ __forceinline__ void gemm_phase(LAS unsigned char* lds, const Gemm g, const StaticOrder& S, const Epi& E) {
;     ...
;             PG8_LDB(B0, 0, 1); PG8_STAGE(PG8_SB(0, 0), b2, voffB); PG8_STAGE(PG8_SA(0, 0), a2, voffA); PG8_STAGE(PG8_SA(0, 1), a2 + hstepA, voffA);
;             PG8_WAIT_V(8); PG8_WAIT_L(0); PG8_BAR; PG8_MMA2B(1, At, At2, B0); PG8_BAR; PG8_SCHED;
;             PG8_LDB(B0, 1, 0); PG8_SCHED; PG8_LDA(At, 1, 0); PG8_LDA(At2, 1, 1); PG8_STAGE(PG8_SB(0, 1), b2 + hstepB, voffB);
;             PG8_WAIT_V(8); PG8_WAIT_L(0); PG8_BAR; PG8_MMA2B(0, At, At2, B0); PG8_BAR; PG8_SCHED;
	ds_read_b128 v[68:71], v222
	ds_read_b128 v[84:87], v222 offset:1024
	ds_read_b128 v[88:91], v222 offset:2048
	ds_read_b128 v[92:95], v222 offset:3072
	s_mov_b32 m0, s48
	s_nop 0
	global_load_lds_dwordx4 v217, s[84:85]
	s_mov_b32 m0, s49
	s_nop 0
	global_load_lds_dwordx4 v219, s[84:85]
	s_mov_b32 m0, s47
	s_nop 0
	global_load_lds_dwordx4 v216, s[14:15]
	s_mov_b32 m0, s50
	s_nop 0
	global_load_lds_dwordx4 v218, s[14:15]
	s_add_u32 s10, s14, 0x40000
	s_addc_u32 s11, s15, 0
	s_mov_b32 m0, s51
	s_nop 0
	global_load_lds_dwordx4 v216, s[10:11]
	s_mov_b32 m0, s52
	s_nop 0
	global_load_lds_dwordx4 v218, s[10:11]
	s_waitcnt vmcnt(8)
	s_waitcnt lgkmcnt(0)
	s_barrier
	v_mfma_f32_16x16x32_bf16 v[72:75], v[68:71], v[96:99], v[72:75]
	v_mfma_f32_16x16x32_bf16 v[56:59], v[88:91], v[96:99], v[56:59]
	v_mfma_f32_16x16x32_bf16 v[44:47], v[88:91], v[152:155], v[44:47]
	v_mfma_f32_16x16x32_bf16 v[36:39], v[88:91], v[166:169], v[36:39]
	v_mfma_f32_16x16x32_bf16 v[128:131], v[68:71], v[182:185], v[128:131]
	v_mfma_f32_16x16x32_bf16 v[32:35], v[88:91], v[182:185], v[32:35]
	v_mfma_f32_16x16x32_bf16 v[116:119], v[68:71], v[190:193], v[116:119]
	v_mfma_f32_16x16x32_bf16 v[20:23], v[88:91], v[190:193], v[20:23]
	v_mfma_f32_16x16x32_bf16 v[108:111], v[68:71], v[198:201], v[108:111]
	v_mfma_f32_16x16x32_bf16 v[12:15], v[88:91], v[198:201], v[12:15]
	v_mfma_f32_16x16x32_bf16 v[104:107], v[68:71], v[226:229], v[104:107]
	v_mfma_f32_16x16x32_bf16 v[8:11], v[88:91], v[226:229], v[8:11]
	v_mfma_f32_16x16x32_bf16 v[60:63], v[68:71], v[234:237], v[60:63]
	v_mfma_f32_16x16x32_bf16 v[0:3], v[88:91], v[234:237], v[0:3]
	v_mfma_f32_16x16x32_bf16 v[72:75], v[84:87], v[100:103], v[72:75]
	v_mfma_f32_16x16x32_bf16 v[56:59], v[92:95], v[100:103], v[56:59]
	v_mfma_f32_16x16x32_bf16 v[96:99], v[68:71], v[152:155], v[140:143]
	v_mfma_f32_16x16x32_bf16 v[44:47], v[92:95], v[156:159], v[44:47]
	v_mfma_f32_16x16x32_bf16 v[100:103], v[68:71], v[166:169], v[132:135]
	v_mfma_f32_16x16x32_bf16 v[36:39], v[92:95], v[178:181], v[36:39]
	v_mfma_f32_16x16x32_bf16 v[128:131], v[84:87], v[186:189], v[128:131]
	v_mfma_f32_16x16x32_bf16 v[32:35], v[92:95], v[186:189], v[32:35]
	v_mfma_f32_16x16x32_bf16 v[116:119], v[84:87], v[194:197], v[116:119]
	v_mfma_f32_16x16x32_bf16 v[20:23], v[92:95], v[194:197], v[20:23]
	v_mfma_f32_16x16x32_bf16 v[108:111], v[84:87], v[202:205], v[108:111]
	v_mfma_f32_16x16x32_bf16 v[12:15], v[92:95], v[202:205], v[12:15]
	v_mfma_f32_16x16x32_bf16 v[104:107], v[84:87], v[230:233], v[104:107]
	v_mfma_f32_16x16x32_bf16 v[8:11], v[92:95], v[230:233], v[8:11]
	v_mfma_f32_16x16x32_bf16 v[60:63], v[84:87], v[238:241], v[60:63]
	v_mfma_f32_16x16x32_bf16 v[0:3], v[92:95], v[238:241], v[0:3]
	v_mfma_f32_16x16x32_bf16 v[96:99], v[84:87], v[156:159], v[96:99]
	v_mfma_f32_16x16x32_bf16 v[100:103], v[84:87], v[178:181], v[100:103]
	s_barrier
	ds_read_b128 v[68:71], v223
	ds_read_b128 v[84:87], v223 offset:1024
	ds_read_b128 v[88:91], v223 offset:2048
	ds_read_b128 v[92:95], v223 offset:3072
	ds_read_b128 v[132:135], v221 offset:32768
	ds_read_b128 v[140:143], v221 offset:33792
	ds_read_b128 v[152:155], v221 offset:34816
	ds_read_b128 v[156:159], v221 offset:35840
	ds_read_b128 v[166:169], v221 offset:36864
	ds_read_b128 v[178:181], v221 offset:37888
	ds_read_b128 v[182:185], v221 offset:38912
	ds_read_b128 v[186:189], v221 offset:39936
	ds_read_b128 v[190:193], v221 offset:49152
	ds_read_b128 v[194:197], v221 offset:50176
	ds_read_b128 v[198:201], v221 offset:51200
	ds_read_b128 v[202:205], v221 offset:52224
	ds_read_b128 v[226:229], v221 offset:53248
	ds_read_b128 v[230:233], v221 offset:54272
	ds_read_b128 v[234:237], v221 offset:55296
	ds_read_b128 v[238:241], v221 offset:56320
	s_add_u32 s10, s84, 0x40000
	s_addc_u32 s11, s85, 0
	s_mov_b32 m0, s53
	s_nop 0
	global_load_lds_dwordx4 v217, s[10:11]
	s_mov_b32 m0, s54
	s_nop 0
	global_load_lds_dwordx4 v219, s[10:11]
	s_waitcnt vmcnt(8)
	s_waitcnt lgkmcnt(0)
	s_barrier
; #define LAS __attribute__((address_space(3)))
; #define PG8_STAGE(bufoff, gbase, voff) do { _Pragma("unroll") for (int _i = 0; _i < 2; ++_i) { \
;         const unsigned _m0 = ldsu + (unsigned)(bufoff) + ldsw + (unsigned)(_i * 8192); \
;         asm volatile("s_mov_b32 m0, %2\n\ts_nop 0\n\tglobal_load_lds_dwordx4 %0, %1" :: "v"((voff)[_i]), "s"((const char*)(gbase)), "s"(_m0) : "memory"); } } while (0)
; #define PG8_LDB(dst, b, h) do { _Pragma("unroll") for (int n = 0; n < 2; ++n) _Pragma("unroll") for (int k = 0; k < 2; ++k) dst[n][k] = *(const LAS bf16x8*)(lds + bbase[b][h] + n * 2048 + k * 1024); } while (0)
; #define PG8_WAIT_V(n) asm volatile("s_waitcnt vmcnt(" #n ")" ::: "memory")
; #define PG8_WAIT_L(n) asm volatile("s_waitcnt lgkmcnt(" #n ")" ::: "memory")
; #define PG8_BAR __builtin_amdgcn_s_barrier()
; #define PG8_SCHED __builtin_amdgcn_sched_barrier(0)
; template <class Epi>
; __device__ __forceinline__ void gemm_phase(LAS unsigned char* lds, const Gemm g, const StaticOrder& S, const Epi& E) {
;     ...
;             PG8_WAIT_V(8); PG8_WAIT_L(0); PG8_BAR; PG8_MMA2B(0, At, At2, B0); PG8_BAR; PG8_SCHED;
;             PG8_LDB(B0, 1, 1); PG8_STAGE(PG8_SB(1, 0), b3, voffB); PG8_STAGE(PG8_SA(1, 0), a3, voffA); PG8_STAGE(PG8_SA(1, 1), a3 + hstepA, voffA);
;     __device__ __forceinline__ void operator()(f32x4 (&acc)[2][2][4][2], const Unit& u, int wr, int wc, int fr, int fq) const {
;     ...
;           else { const int which = t >> 6, j = (t & 63) * 4, bj = j >> 7, c = j & 127; const float* src = (which < 3 ? cw + (size_t)which * NUP : cb) + bj * DFF + u.pn * 128 + c;
;               *(LAS f32x4*)(cwL + which * 256 + j) = *(const f32x4*)src; } }
	v_mfma_f32_16x16x32_bf16 v[80:83], v[68:71], v[132:135], v[80:83]
	v_mfma_f32_16x16x32_bf16 v[76:79], v[88:91], v[132:135], v[76:79]
	v_mfma_f32_16x16x32_bf16 v[148:151], v[68:71], v[152:155], v[148:151]
	v_mfma_f32_16x16x32_bf16 v[52:55], v[88:91], v[152:155], v[52:55]
	v_mfma_f32_16x16x32_bf16 v[144:147], v[68:71], v[166:169], v[144:147]
	v_mfma_f32_16x16x32_bf16 v[48:51], v[88:91], v[166:169], v[48:51]
	v_mfma_f32_16x16x32_bf16 v[136:139], v[68:71], v[182:185], v[136:139]
	v_mfma_f32_16x16x32_bf16 v[40:43], v[88:91], v[182:185], v[40:43]
	v_mfma_f32_16x16x32_bf16 v[124:127], v[68:71], v[190:193], v[124:127]
	v_mfma_f32_16x16x32_bf16 v[28:31], v[88:91], v[190:193], v[28:31]
	v_mfma_f32_16x16x32_bf16 v[120:123], v[68:71], v[198:201], v[120:123]
	v_mfma_f32_16x16x32_bf16 v[24:27], v[88:91], v[198:201], v[24:27]
	v_mfma_f32_16x16x32_bf16 v[112:115], v[68:71], v[226:229], v[112:115]
	v_mfma_f32_16x16x32_bf16 v[16:19], v[88:91], v[226:229], v[16:19]
	v_mfma_f32_16x16x32_bf16 v[64:67], v[68:71], v[234:237], v[64:67]
	v_mfma_f32_16x16x32_bf16 v[4:7], v[88:91], v[234:237], v[4:7]
	v_mfma_f32_16x16x32_bf16 v[80:83], v[84:87], v[140:143], v[80:83]
	v_mfma_f32_16x16x32_bf16 v[76:79], v[92:95], v[140:143], v[76:79]
	v_mfma_f32_16x16x32_bf16 v[148:151], v[84:87], v[156:159], v[148:151]
	v_mfma_f32_16x16x32_bf16 v[52:55], v[92:95], v[156:159], v[52:55]
	v_mfma_f32_16x16x32_bf16 v[144:147], v[84:87], v[178:181], v[144:147]
	v_mfma_f32_16x16x32_bf16 v[48:51], v[92:95], v[178:181], v[48:51]
	v_mfma_f32_16x16x32_bf16 v[136:139], v[84:87], v[186:189], v[136:139]
	v_mfma_f32_16x16x32_bf16 v[40:43], v[92:95], v[186:189], v[40:43]
	v_mfma_f32_16x16x32_bf16 v[124:127], v[84:87], v[194:197], v[124:127]
	v_mfma_f32_16x16x32_bf16 v[28:31], v[92:95], v[194:197], v[28:31]
	v_mfma_f32_16x16x32_bf16 v[120:123], v[84:87], v[202:205], v[120:123]
	v_mfma_f32_16x16x32_bf16 v[24:27], v[92:95], v[202:205], v[24:27]
	v_mfma_f32_16x16x32_bf16 v[112:115], v[84:87], v[230:233], v[112:115]
	v_mfma_f32_16x16x32_bf16 v[16:19], v[92:95], v[230:233], v[16:19]
	v_mfma_f32_16x16x32_bf16 v[64:67], v[84:87], v[238:241], v[64:67]
	v_mfma_f32_16x16x32_bf16 v[4:7], v[92:95], v[238:241], v[4:7]
	s_barrier
	s_add_u32 s10, s84, 0x80
	ds_read_b128 v[68:71], v224
	ds_read_b128 v[84:87], v224 offset:1024
	ds_read_b128 v[88:91], v224 offset:2048
	ds_read_b128 v[92:95], v224 offset:3072
	s_addc_u32 s11, s85, 0
	s_mov_b32 m0, s88
	s_nop 0
	global_load_lds_dwordx4 v217, s[10:11]
	s_mov_b32 m0, s89
	s_nop 0
	global_load_lds_dwordx4 v219, s[10:11]
	s_mov_b32 m0, s95
	s_nop 0
	global_load_lds_dwordx4 v216, s[16:17]
	s_mov_b32 m0, s37
	s_nop 0
	global_load_lds_dwordx4 v218, s[16:17]
	s_add_u32 s10, s14, 0x40080
	s_addc_u32 s11, s15, 0
	s_mov_b32 m0, s56
	s_nop 0
	global_load_lds_dwordx4 v216, s[10:11]
	s_mov_b32 m0, s57
	s_nop 0
	global_load_lds_dwordx4 v218, s[10:11]
	s_cmp_eq_u32 s69, 12
	s_cbranch_scc0 .Lcw_skip
	s_cmp_eq_u64 s[4:5], 0
	s_cbranch_scc1 .Lcw_skip
	v_lshlrev_b32_e32 v242, 4, v215
	v_add3_u32 v242, v214, s59, v242
	s_lshr_b32 s32, s59, 6
	s_mul_i32 s98, s32, 0x5800
	s_add_u32 s98, s0, s98
	s_addc_u32 s99, s1, 0
	s_cmp_lt_u32 s32, 3
	s_cselect_b32 s98, s98, s2
	s_cselect_b32 s99, s99, s3
	s_lshl_b32 s32, s67, 9
	s_add_u32 s98, s98, s32
	s_addc_u32 s99, s99, 0
	v_bfe_u32 v243, v242, 5, 1
	v_mul_u32_u24_e32 v243, 0x2c00, v243
	v_and_b32_e32 v244, 31, v242
	v_lshl_add_u32 v243, v244, 4, v243
	v_readlane_b32 s32, v252, 44
	s_nop 3
	s_lshl_b32 m0, s59, 4
	s_add_u32 m0, m0, s32
	s_nop 0
	global_load_lds_dwordx4 v243, s[98:99]

; #define LAS __attribute__((address_space(3)))
; __device__ __forceinline__ unsigned cvt_pk_bf16(float lo, float hi) { unsigned r; asm volatile("v_cvt_pk_bf16_f32 %0, %1, %2" : "=v"(r) : "v"(lo), "v"(hi)); return r; }
; __device__ __forceinline__ float sigm(float x) { return __builtin_amdgcn_rcpf(1.0f + __expf(-x)); }
; __device__ __forceinline__ int opq(int v) { asm volatile("" : "+v"(v)); return v; }
;     __device__ __forceinline__ void operator()(f32x4 (&acc)[2][2][4][2], const Unit& u, int wr, int wc, int fr, int fq) const {
;     ...
;         EPI_FOR_ROWS() { const float rs = rsL[ai * 128 + wr * 64 + m * 16 + fr];
; #pragma unroll
;             for (int bj = 0; bj < 2; ++bj) { acc[ai][bj][m][0] *= rs; acc[ai][bj][m][1] *= rs; } }
;     ...
;                         const f32x4 cur = acc[ai][bj][m][n]; f32x4 p1 = ror4(cur, 1), p2 = ror4(cur, 2);
;                         if (m > 0) { const f32x4 pv = acc[ai][bj][m - 1][n]; const f32x4 q1 = ror4(pv, 1), q2 = ror4(pv, 2);
; #pragma unroll
;                             for (int e = 0; e < 4; ++e) { p1[e] = (fr == 0) ? q1[e] : p1[e]; p2[e] = (fr < 2) ? q2[e] : p2[e]; } }
;                         else { f32x4 h14 = (f32x4){0.f, 0.f, 0.f, 0.f}, h15 = h14;
;                             if (!(wr == 0 && ai == 0)) { const int sai = (wr == 1) ? ai : 0, swr = (wr == 1) ? 0 : 1; const int ox = opq(0);
;                                 const LAS float* hp = hl + (((((sai * 2 + swr) * 4 + wc) * 2 + 0) * 2 + bj) * 32 + 8 * fq + 4 * n) + ox;
;                                 const float r14 = rsL[sai * 128 + swr * 64 + 62 + ox], r15 = rsL[sai * 128 + swr * 64 + 63 + ox];
;                                 h14 = *(const LAS f32x4*)hp * r14; h15 = *(const LAS f32x4*)(hp + 64) * r15; }
; #pragma unroll
;                             for (int e = 0; e < 4; ++e) { p1[e] = (fr == 0) ? h15[e] : p1[e]; p2[e] = (fr == 0) ? h14[e] : ((fr == 1) ? h15[e] : p2[e]); } }
;                         const f32x4 w0 = bj ? wv0 : wg0, w1 = bj ? wv1 : wg1, w2 = bj ? wv2 : wg2, bb = bj ? bv : bg;
;                         gv[bj] = bb + w0 * p2 + w1 * p1 + w2 * cur;
;                     }
;                     float o[4];
; #pragma unroll
;                     for (int e = 0; e < 4; ++e) o[e] = gv[0][e] * sigm(gv[0][e]) * gv[1][e];
;                     u32x2 w; w.x = cvt_pk_bf16(o[0], o[1]); w.y = cvt_pk_bf16(o[2], o[3]);
.LBB0_1054:
	s_or_b64 exec, exec, s[16:17]
	v_mov_b32_e32 v98, v182
	v_mov_b32_e32 v99, v182
	v_mov_b32_e32 v118, v185
	v_mov_b32_e32 v119, v185
	v_mov_b32_e32 v184, v185
	v_mov_b32_e32 v100, v183
	v_mov_b32_e32 v101, v183
	v_pk_mul_f32 v[54:55], v[54:55], v[118:119]
	v_pk_mul_f32 v[118:119], v[46:47], v[118:119]
	v_pk_mul_f32 v[48:49], v[48:49], v[98:99]
	v_pk_mul_f32 v[46:47], v[36:37], v[98:99]
	v_mov_b32_e32 v98, v180
	v_mov_b32_e32 v99, v180
	v_mov_b32_e32 v102, v180
	v_mov_b32_e32 v103, v180
	v_mov_b32_e32 v116, v181
	v_mov_b32_e32 v117, v181
	v_mov_b32_e32 v179, v178
	v_pk_mul_f32 v[120:121], v[44:45], v[184:185]
	v_mov_b32_e32 v44, v182
	v_mov_b32_e32 v45, v182
	v_mov_b32_e32 v182, v183
	v_pk_mul_f32 v[36:37], v[32:33], v[100:101]
	v_pk_mul_f32 v[32:33], v[30:31], v[98:99]
	v_pk_mul_f32 v[30:31], v[22:23], v[98:99]
	v_mov_b32_e32 v180, v181
	v_mov_b32_e32 v98, v178
	v_mov_b32_e32 v99, v178
	v_pk_mul_f32 v[52:53], v[52:53], v[184:185]
	v_pk_mul_f32 v[50:51], v[50:51], v[44:45]
	v_pk_mul_f32 v[44:45], v[38:39], v[44:45]
	v_pk_mul_f32 v[42:43], v[42:43], v[182:183]
	v_pk_mul_f32 v[40:41], v[40:41], v[100:101]
	v_pk_mul_f32 v[38:39], v[34:35], v[182:183]
	v_pk_mul_f32 v[34:35], v[28:29], v[102:103]
	v_pk_mul_f32 v[28:29], v[20:21], v[102:103]
	v_pk_mul_f32 v[26:27], v[26:27], v[180:181]
	v_pk_mul_f32 v[24:25], v[24:25], v[116:117]
	v_pk_mul_f32 v[20:21], v[14:15], v[180:181]
	v_pk_mul_f32 v[22:23], v[12:13], v[116:117]
	v_pk_mul_f32 v[12:13], v[18:19], v[98:99]
	v_pk_mul_f32 v[14:15], v[16:17], v[178:179]
	v_pk_mul_f32 v[10:11], v[10:11], v[98:99]
	v_pk_mul_f32 v[8:9], v[8:9], v[178:179]
	v_mov_b32_dpp v102, v52 row_ror:2 row_mask:0xf bank_mask:0xf
	v_mov_b32_dpp v103, v53 row_ror:2 row_mask:0xf bank_mask:0xf
	v_mov_b32_dpp v98, v52 row_ror:1 row_mask:0xf bank_mask:0xf
	v_mov_b32_dpp v99, v53 row_ror:1 row_mask:0xf bank_mask:0xf
	v_mov_b32_dpp v100, v54 row_ror:1 row_mask:0xf bank_mask:0xf
	v_mov_b32_dpp v101, v55 row_ror:1 row_mask:0xf bank_mask:0xf
	v_mov_b32_dpp v116, v54 row_ror:2 row_mask:0xf bank_mask:0xf
	v_mov_b32_dpp v117, v55 row_ror:2 row_mask:0xf bank_mask:0xf
	v_mov_b32_dpp v122, v60 row_ror:1 row_mask:0xf bank_mask:0xf
	v_mov_b32_dpp v123, v61 row_ror:1 row_mask:0xf bank_mask:0xf
	v_mov_b32_dpp v124, v62 row_ror:1 row_mask:0xf bank_mask:0xf
	v_mov_b32_dpp v125, v63 row_ror:1 row_mask:0xf bank_mask:0xf
	v_mov_b32_dpp v60, v60 row_ror:2 row_mask:0xf bank_mask:0xf
	v_mov_b32_dpp v61, v61 row_ror:2 row_mask:0xf bank_mask:0xf
	v_mov_b32_dpp v62, v62 row_ror:2 row_mask:0xf bank_mask:0xf
	v_mov_b32_dpp v63, v63 row_ror:2 row_mask:0xf bank_mask:0xf
	v_cndmask_b32_e64 v18, v102, v60, s[10:11]
	v_cndmask_b32_e64 v19, v103, v61, s[10:11]
	v_cndmask_b32_e64 v17, v117, v63, s[10:11]
	v_cndmask_b32_e64 v16, v116, v62, s[10:11]
	v_cndmask_b32_e64 v61, v101, v125, s[12:13]
	v_cndmask_b32_e64 v62, v98, v122, s[12:13]
	v_cndmask_b32_e64 v63, v99, v123, s[12:13]
	v_cndmask_b32_e64 v60, v100, v124, s[12:13]
	v_pk_fma_f32 v[18:19], v[88:89], v[18:19], v[92:93]
	v_mov_b32_dpp v124, v118 row_ror:2 row_mask:0xf bank_mask:0xf
	v_mov_b32_dpp v125, v119 row_ror:2 row_mask:0xf bank_mask:0xf
	v_pk_fma_f32 v[16:17], v[90:91], v[16:17], v[94:95]
	v_pk_fma_f32 v[18:19], v[80:81], v[62:63], v[18:19]
	v_mov_b32_dpp v62, v118 row_ror:1 row_mask:0xf bank_mask:0xf
	v_mov_b32_dpp v63, v119 row_ror:1 row_mask:0xf bank_mask:0xf
	v_mov_b32_dpp v122, v120 row_ror:2 row_mask:0xf bank_mask:0xf
	v_mov_b32_dpp v123, v121 row_ror:2 row_mask:0xf bank_mask:0xf
	v_mov_b32_dpp v128, v58 row_ror:1 row_mask:0xf bank_mask:0xf
	v_mov_b32_dpp v129, v59 row_ror:1 row_mask:0xf bank_mask:0xf
	v_mov_b32_dpp v58, v58 row_ror:2 row_mask:0xf bank_mask:0xf
	v_mov_b32_dpp v59, v59 row_ror:2 row_mask:0xf bank_mask:0xf
	v_pk_fma_f32 v[16:17], v[82:83], v[60:61], v[16:17]
	v_pk_fma_f32 v[18:19], v[52:53], v[84:85], v[18:19]
	v_mov_b32_dpp v126, v56 row_ror:1 row_mask:0xf bank_mask:0xf
	v_mov_b32_dpp v127, v57 row_ror:1 row_mask:0xf bank_mask:0xf
	v_mov_b32_dpp v56, v56 row_ror:2 row_mask:0xf bank_mask:0xf
	v_mov_b32_dpp v57, v57 row_ror:2 row_mask:0xf bank_mask:0xf
	v_cndmask_b32_e64 v53, v125, v59, s[10:11]
	v_cndmask_b32_e64 v52, v124, v58, s[10:11]
	v_pk_fma_f32 v[16:17], v[54:55], v[86:87], v[16:17]
	v_cndmask_b32_e64 v54, v122, v56, s[10:11]
	v_cndmask_b32_e64 v55, v123, v57, s[10:11]
	v_cndmask_b32_e64 v57, v63, v129, s[12:13]
	v_cndmask_b32_e64 v56, v62, v128, s[12:13]
	v_pk_fma_f32 v[52:53], v[74:75], v[52:53], v[78:79]
	v_mov_b32_dpp v60, v120 row_ror:1 row_mask:0xf bank_mask:0xf
	v_pk_fma_f32 v[52:53], v[70:71], v[56:57], v[52:53]
	v_mul_f32_e32 v56, 0xbfb8aa3b, v18
	v_exp_f32_e32 v56, v56
	v_mov_b32_dpp v61, v121 row_ror:1 row_mask:0xf bank_mask:0xf
	v_add_f32_e32 v56, 1.0, v56
	v_rcp_f32_e32 v56, v56
	v_cndmask_b32_e64 v58, v60, v126, s[12:13]
	v_cndmask_b32_e64 v59, v61, v127, s[12:13]
	v_pk_fma_f32 v[54:55], v[72:73], v[54:55], v[76:77]
	v_mul_f32_e32 v18, v18, v56
	v_pk_fma_f32 v[54:55], v[68:69], v[58:59], v[54:55]
	v_pk_fma_f32 v[52:53], v[118:119], v[66:67], v[52:53]
	v_pk_fma_f32 v[54:55], v[120:121], v[64:65], v[54:55]
	s_nop 0
	v_mul_f32_e32 v18, v18, v54
	v_mul_f32_e32 v54, 0xbfb8aa3b, v19
	v_exp_f32_e32 v54, v54
	s_nop 0
	v_add_f32_e32 v54, 1.0, v54
	v_rcp_f32_e32 v54, v54
	s_nop 0
	v_mul_f32_e32 v19, v19, v54
	v_mul_f32_e32 v54, 0xbfb8aa3b, v16
	v_exp_f32_e32 v54, v54
	v_mul_f32_e32 v19, v19, v55
	v_add_f32_e32 v54, 1.0, v54
	v_rcp_f32_e32 v54, v54
	s_nop 0
	v_mul_f32_e32 v16, v16, v54
	v_mul_f32_e32 v52, v16, v52
	v_mul_f32_e32 v16, 0xbfb8aa3b, v17
	v_exp_f32_e32 v16, v16
	s_nop 0
	v_add_f32_e32 v16, 1.0, v16
	v_rcp_f32_e32 v16, v16
	s_nop 0
	v_mul_f32_e32 v16, v17, v16
; #define LAS __attribute__((address_space(3)))
; __device__ __forceinline__ unsigned cvt_pk_bf16(float lo, float hi) { unsigned r; asm volatile("v_cvt_pk_bf16_f32 %0, %1, %2" : "=v"(r) : "v"(lo), "v"(hi)); return r; }
; __device__ __forceinline__ float sigm(float x) { return __builtin_amdgcn_rcpf(1.0f + __expf(-x)); }
; __device__ __forceinline__ int opq(int v) { asm volatile("" : "+v"(v)); return v; }
;     __device__ __forceinline__ void operator()(f32x4 (&acc)[2][2][4][2], const Unit& u, int wr, int wc, int fr, int fq) const {
;     ...
;                         const f32x4 cur = acc[ai][bj][m][n]; f32x4 p1 = ror4(cur, 1), p2 = ror4(cur, 2);
;                         if (m > 0) { const f32x4 pv = acc[ai][bj][m - 1][n]; const f32x4 q1 = ror4(pv, 1), q2 = ror4(pv, 2);
; #pragma unroll
;                             for (int e = 0; e < 4; ++e) { p1[e] = (fr == 0) ? q1[e] : p1[e]; p2[e] = (fr < 2) ? q2[e] : p2[e]; } }
;                         else { f32x4 h14 = (f32x4){0.f, 0.f, 0.f, 0.f}, h15 = h14;
;                             if (!(wr == 0 && ai == 0)) { const int sai = (wr == 1) ? ai : 0, swr = (wr == 1) ? 0 : 1; const int ox = opq(0);
;                                 const LAS float* hp = hl + (((((sai * 2 + swr) * 4 + wc) * 2 + 0) * 2 + bj) * 32 + 8 * fq + 4 * n) + ox;
;                                 const float r14 = rsL[sai * 128 + swr * 64 + 62 + ox], r15 = rsL[sai * 128 + swr * 64 + 63 + ox];
;                                 h14 = *(const LAS f32x4*)hp * r14; h15 = *(const LAS f32x4*)(hp + 64) * r15; }
; #pragma unroll
;                             for (int e = 0; e < 4; ++e) { p1[e] = (fr == 0) ? h15[e] : p1[e]; p2[e] = (fr == 0) ? h14[e] : ((fr == 1) ? h15[e] : p2[e]); } }
;                         const f32x4 w0 = bj ? wv0 : wg0, w1 = bj ? wv1 : wg1, w2 = bj ? wv2 : wg2, bb = bj ? bv : bg;
;                         gv[bj] = bb + w0 * p2 + w1 * p1 + w2 * cur;
;                     }
;                     float o[4];
; #pragma unroll
;                     for (int e = 0; e < 4; ++e) o[e] = gv[0][e] * sigm(gv[0][e]) * gv[1][e];
;                     u32x2 w; w.x = cvt_pk_bf16(o[0], o[1]); w.y = cvt_pk_bf16(o[2], o[3]);
;                     const bool edge = (wr == 0 && ai == 0 && m == 0 && fr < 2 && !seq0);
;                     if (!edge) *(u32x2*)(act + (size_t)(row0 + ai * 128 + m * 16) * DFF + colg0 + 4 * n) = w;
	v_mul_f32_e32 v17, v16, v53
	v_cvt_pk_bf16_f32 v16, v18, v19
	v_cvt_pk_bf16_f32 v17, v52, v17
	global_store_dwordx2 v[104:105], v[16:17], off offset:8
	v_mov_b32_dpp v104, v48 row_ror:2 row_mask:0xf bank_mask:0xf
	v_mov_b32_dpp v105, v49 row_ror:2 row_mask:0xf bank_mask:0xf
	v_mov_b32_dpp v56, v48 row_ror:1 row_mask:0xf bank_mask:0xf
	v_mov_b32_dpp v57, v49 row_ror:1 row_mask:0xf bank_mask:0xf
	v_mov_b32_dpp v118, v50 row_ror:2 row_mask:0xf bank_mask:0xf
	v_mov_b32_dpp v119, v51 row_ror:2 row_mask:0xf bank_mask:0xf
	v_mov_b32_dpp v58, v50 row_ror:1 row_mask:0xf bank_mask:0xf
	v_mov_b32_dpp v59, v51 row_ror:1 row_mask:0xf bank_mask:0xf
	v_cndmask_b32_e64 v18, v104, v102, s[10:11]
	v_cndmask_b32_e64 v19, v105, v103, s[10:11]
	v_cndmask_b32_e64 v17, v119, v117, s[10:11]
	v_cndmask_b32_e64 v16, v118, v116, s[10:11]
	v_cndmask_b32_e64 v54, v56, v98, s[12:13]
	v_cndmask_b32_e64 v55, v57, v99, s[12:13]
	v_pk_fma_f32 v[18:19], v[88:89], v[18:19], v[92:93]
	v_mov_b32_dpp v116, v44 row_ror:2 row_mask:0xf bank_mask:0xf
	v_mov_b32_dpp v117, v45 row_ror:2 row_mask:0xf bank_mask:0xf
	v_cndmask_b32_e64 v53, v59, v101, s[12:13]
	v_cndmask_b32_e64 v52, v58, v100, s[12:13]
	v_pk_fma_f32 v[18:19], v[80:81], v[54:55], v[18:19]
	v_mov_b32_dpp v100, v44 row_ror:1 row_mask:0xf bank_mask:0xf
	v_mov_b32_dpp v101, v45 row_ror:1 row_mask:0xf bank_mask:0xf
	v_pk_fma_f32 v[16:17], v[90:91], v[16:17], v[94:95]
	v_pk_fma_f32 v[18:19], v[48:49], v[84:85], v[18:19]
	v_cndmask_b32_e64 v49, v117, v125, s[10:11]
	v_cndmask_b32_e64 v48, v116, v124, s[10:11]
	v_pk_fma_f32 v[16:17], v[82:83], v[52:53], v[16:17]
	v_cndmask_b32_e64 v53, v101, v63, s[12:13]
	v_cndmask_b32_e64 v52, v100, v62, s[12:13]
	v_pk_fma_f32 v[48:49], v[74:75], v[48:49], v[78:79]
	v_mov_b32_dpp v102, v46 row_ror:2 row_mask:0xf bank_mask:0xf
	v_pk_fma_f32 v[48:49], v[70:71], v[52:53], v[48:49]
	v_mov_b32_dpp v103, v47 row_ror:2 row_mask:0xf bank_mask:0xf
	v_pk_fma_f32 v[44:45], v[44:45], v[66:67], v[48:49]
	v_mul_f32_e32 v48, 0xbfb8aa3b, v18
	v_exp_f32_e32 v48, v48
	v_mov_b32_dpp v98, v46 row_ror:1 row_mask:0xf bank_mask:0xf
	v_mov_b32_dpp v99, v47 row_ror:1 row_mask:0xf bank_mask:0xf
	v_add_f32_e32 v48, 1.0, v48
	v_rcp_f32_e32 v48, v48
	v_pk_fma_f32 v[16:17], v[50:51], v[86:87], v[16:17]
	v_cndmask_b32_e64 v50, v102, v122, s[10:11]
	v_cndmask_b32_e64 v51, v103, v123, s[10:11]
	v_cndmask_b32_e64 v54, v98, v60, s[12:13]
	v_cndmask_b32_e64 v55, v99, v61, s[12:13]
	v_pk_fma_f32 v[50:51], v[72:73], v[50:51], v[76:77]
	v_mul_f32_e32 v18, v18, v48
	v_pk_fma_f32 v[50:51], v[68:69], v[54:55], v[50:51]
	s_nop 0
	v_pk_fma_f32 v[46:47], v[46:47], v[64:65], v[50:51]
	s_nop 0
	v_mul_f32_e32 v18, v18, v46
	v_mul_f32_e32 v46, 0xbfb8aa3b, v19
	v_exp_f32_e32 v46, v46
	s_nop 0
	v_add_f32_e32 v46, 1.0, v46
	v_rcp_f32_e32 v46, v46
	s_nop 0
	v_mul_f32_e32 v19, v19, v46
	v_mul_f32_e32 v46, 0xbfb8aa3b, v16
	v_exp_f32_e32 v46, v46
	v_mul_f32_e32 v19, v19, v47
	v_add_f32_e32 v46, 1.0, v46
	v_rcp_f32_e32 v46, v46
	s_nop 0
	v_mul_f32_e32 v16, v16, v46
	v_mul_f32_e32 v44, v16, v44
	v_mul_f32_e32 v16, 0xbfb8aa3b, v17
	v_exp_f32_e32 v16, v16
	s_nop 0
	v_add_f32_e32 v16, 1.0, v16
	v_rcp_f32_e32 v16, v16
	s_nop 0
	v_mul_f32_e32 v16, v17, v16
	v_mul_f32_e32 v17, v16, v45
	v_cvt_pk_bf16_f32 v16, v18, v19
	v_cvt_pk_bf16_f32 v17, v44, v17
	global_store_dwordx2 v[106:107], v[16:17], off offset:8
	v_mov_b32_dpp v16, v40 row_ror:2 row_mask:0xf bank_mask:0xf
	v_mov_b32_dpp v19, v41 row_ror:2 row_mask:0xf bank_mask:0xf
	v_mov_b32_dpp v44, v40 row_ror:1 row_mask:0xf bank_mask:0xf
	v_mov_b32_dpp v47, v41 row_ror:1 row_mask:0xf bank_mask:0xf
	v_mov_b32_dpp v46, v42 row_ror:2 row_mask:0xf bank_mask:0xf
	v_mov_b32_dpp v17, v43 row_ror:2 row_mask:0xf bank_mask:0xf
	v_mov_b32_dpp v48, v42 row_ror:1 row_mask:0xf bank_mask:0xf
	v_mov_b32_dpp v45, v43 row_ror:1 row_mask:0xf bank_mask:0xf
	v_cndmask_b32_e64 v18, v16, v104, s[10:11]
	v_cndmask_b32_e64 v19, v19, v105, s[10:11]
	v_cndmask_b32_e64 v17, v17, v119, s[10:11]
	v_cndmask_b32_e64 v16, v46, v118, s[10:11]
	v_cndmask_b32_e64 v46, v44, v56, s[12:13]
	v_cndmask_b32_e64 v47, v47, v57, s[12:13]
	v_pk_fma_f32 v[18:19], v[88:89], v[18:19], v[92:93]
	v_cndmask_b32_e64 v45, v45, v59, s[12:13]
	v_cndmask_b32_e64 v44, v48, v58, s[12:13]
	v_pk_fma_f32 v[16:17], v[90:91], v[16:17], v[94:95]
	v_pk_fma_f32 v[18:19], v[80:81], v[46:47], v[18:19]
	v_pk_fma_f32 v[16:17], v[82:83], v[44:45], v[16:17]
	v_pk_fma_f32 v[18:19], v[40:41], v[84:85], v[18:19]
	v_mov_b32_dpp v44, v36 row_ror:1 row_mask:0xf bank_mask:0xf
	v_mov_b32_dpp v48, v38 row_ror:1 row_mask:0xf bank_mask:0xf
	v_mov_b32_dpp v40, v36 row_ror:2 row_mask:0xf bank_mask:0xf
	v_mov_b32_dpp v46, v38 row_ror:2 row_mask:0xf bank_mask:0xf
	v_pk_fma_f32 v[16:17], v[42:43], v[86:87], v[16:17]
	v_mov_b32_dpp v41, v39 row_ror:2 row_mask:0xf bank_mask:0xf
	v_cndmask_b32_e64 v42, v40, v102, s[10:11]
	v_cndmask_b32_e64 v40, v46, v116, s[10:11]
	v_cndmask_b32_e64 v46, v44, v98, s[12:13]
	v_cndmask_b32_e64 v44, v48, v100, s[12:13]
	v_mul_f32_e32 v48, 0xbfb8aa3b, v18
	v_mov_b32_dpp v45, v39 row_ror:1 row_mask:0xf bank_mask:0xf
	v_exp_f32_e32 v48, v48
	v_cndmask_b32_e64 v41, v41, v117, s[10:11]
	v_cndmask_b32_e64 v45, v45, v101, s[12:13]
	v_pk_fma_f32 v[40:41], v[74:75], v[40:41], v[78:79]
	v_mov_b32_dpp v43, v37 row_ror:2 row_mask:0xf bank_mask:0xf
	v_pk_fma_f32 v[40:41], v[70:71], v[44:45], v[40:41]
	v_mov_b32_dpp v47, v37 row_ror:1 row_mask:0xf bank_mask:0xf
	v_pk_fma_f32 v[38:39], v[38:39], v[66:67], v[40:41]
	v_add_f32_e32 v40, 1.0, v48
	v_rcp_f32_e32 v40, v40
	v_mul_f32_e32 v41, 0xbfb8aa3b, v19
	v_cndmask_b32_e64 v43, v43, v103, s[10:11]
	v_exp_f32_e32 v41, v41
	v_cndmask_b32_e64 v47, v47, v99, s[12:13]
	v_pk_fma_f32 v[42:43], v[72:73], v[42:43], v[76:77]
	v_mul_f32_e32 v18, v18, v40
	v_pk_fma_f32 v[42:43], v[68:69], v[46:47], v[42:43]
	v_mul_f32_e32 v40, 0xbfb8aa3b, v16
	v_pk_fma_f32 v[36:37], v[36:37], v[64:65], v[42:43]
	v_exp_f32_e32 v40, v40
	v_mul_f32_e32 v18, v18, v36
	v_add_f32_e32 v36, 1.0, v41
	v_rcp_f32_e32 v36, v36
	v_mul_f32_e32 v41, 0xbfb8aa3b, v17
	v_exp_f32_e32 v41, v41
	v_mul_f32_e32 v19, v19, v36
	v_add_f32_e32 v36, 1.0, v40
	v_rcp_f32_e32 v36, v36
	v_add_f32_e32 v40, 1.0, v41
	v_rcp_f32_e32 v40, v40
	v_mul_f32_e32 v19, v19, v37
	v_mul_f32_e32 v16, v16, v36
	v_mul_f32_e32 v36, v16, v38
	v_mul_f32_e32 v16, v17, v40
	v_mul_f32_e32 v17, v16, v39
	v_cvt_pk_bf16_f32 v16, v18, v19
	v_cvt_pk_bf16_f32 v17, v36, v17
	global_store_dwordx2 v[108:109], v[16:17], off offset:8
	v_mov_b32_e32 v16, v161
	v_mov_b32_dpp v42, v34 row_ror:1 row_mask:0xf bank_mask:0xf
	v_lshlrev_b32_e32 v16, 2, v16
	v_add_u32_e32 v36, v142, v16
	v_add_u32_e32 v16, s62, v16
	ds_read2_b32 v[40:41], v16 offset0:62 offset1:63
	ds_read_b128 v[16:19], v36 offset:16
	ds_read_b128 v[36:39], v36 offset:272
	v_mov_b32_dpp v46, v34 row_ror:2 row_mask:0xf bank_mask:0xf
	v_mov_b32_dpp v47, v35 row_ror:2 row_mask:0xf bank_mask:0xf
	s_waitcnt lgkmcnt(0)
; #define LAS __attribute__((address_space(3)))
; __device__ __forceinline__ unsigned cvt_pk_bf16(float lo, float hi) { unsigned r; asm volatile("v_cvt_pk_bf16_f32 %0, %1, %2" : "=v"(r) : "v"(lo), "v"(hi)); return r; }
; __device__ __forceinline__ float sigm(float x) { return __builtin_amdgcn_rcpf(1.0f + __expf(-x)); }
; __device__ __forceinline__ int opq(int v) { asm volatile("" : "+v"(v)); return v; }
;     __device__ __forceinline__ void operator()(f32x4 (&acc)[2][2][4][2], const Unit& u, int wr, int wc, int fr, int fq) const {
;     ...
;                         const f32x4 cur = acc[ai][bj][m][n]; f32x4 p1 = ror4(cur, 1), p2 = ror4(cur, 2);
;                         if (m > 0) { const f32x4 pv = acc[ai][bj][m - 1][n]; const f32x4 q1 = ror4(pv, 1), q2 = ror4(pv, 2);
; #pragma unroll
;                             for (int e = 0; e < 4; ++e) { p1[e] = (fr == 0) ? q1[e] : p1[e]; p2[e] = (fr < 2) ? q2[e] : p2[e]; } }
;                         else { f32x4 h14 = (f32x4){0.f, 0.f, 0.f, 0.f}, h15 = h14;
;                             if (!(wr == 0 && ai == 0)) { const int sai = (wr == 1) ? ai : 0, swr = (wr == 1) ? 0 : 1; const int ox = opq(0);
;                                 const LAS float* hp = hl + (((((sai * 2 + swr) * 4 + wc) * 2 + 0) * 2 + bj) * 32 + 8 * fq + 4 * n) + ox;
;                                 const float r14 = rsL[sai * 128 + swr * 64 + 62 + ox], r15 = rsL[sai * 128 + swr * 64 + 63 + ox];
;                                 h14 = *(const LAS f32x4*)hp * r14; h15 = *(const LAS f32x4*)(hp + 64) * r15; }
; #pragma unroll
;                             for (int e = 0; e < 4; ++e) { p1[e] = (fr == 0) ? h15[e] : p1[e]; p2[e] = (fr == 0) ? h14[e] : ((fr == 1) ? h15[e] : p2[e]); } }
;                         const f32x4 w0 = bj ? wv0 : wg0, w1 = bj ? wv1 : wg1, w2 = bj ? wv2 : wg2, bb = bj ? bv : bg;
;                         gv[bj] = bb + w0 * p2 + w1 * p1 + w2 * cur;
;                     }
;                     float o[4];
; #pragma unroll
;                     for (int e = 0; e < 4; ++e) o[e] = gv[0][e] * sigm(gv[0][e]) * gv[1][e];
;                     u32x2 w; w.x = cvt_pk_bf16(o[0], o[1]); w.y = cvt_pk_bf16(o[2], o[3]);
;                     const bool edge = (wr == 0 && ai == 0 && m == 0 && fr < 2 && !seq0);
;                     if (!edge) *(u32x2*)(act + (size_t)(row0 + ai * 128 + m * 16) * DFF + colg0 + 4 * n) = w;
	v_pk_mul_f32 v[36:37], v[36:37], v[40:41] op_sel:[0,1]
	v_pk_mul_f32 v[18:19], v[18:19], v[40:41] op_sel_hi:[1,0]
	v_pk_mul_f32 v[16:17], v[16:17], v[40:41] op_sel_hi:[1,0]
	v_pk_mul_f32 v[38:39], v[38:39], v[40:41] op_sel:[0,1]
	v_cndmask_b32_e64 v40, v42, v36, s[12:13]
	v_cndmask_b32_e64 v36, v46, v36, s[14:15]
	v_mov_b32_dpp v43, v35 row_ror:1 row_mask:0xf bank_mask:0xf
	v_cndmask_b32_e64 v16, v36, v16, s[12:13]
	v_cndmask_b32_e64 v36, v47, v37, s[14:15]
	v_mov_b32_dpp v44, v32 row_ror:1 row_mask:0xf bank_mask:0xf
	v_mov_b32_dpp v48, v32 row_ror:2 row_mask:0xf bank_mask:0xf
	v_mov_b32_dpp v49, v33 row_ror:2 row_mask:0xf bank_mask:0xf
	v_cndmask_b32_e64 v17, v36, v17, s[12:13]
	v_mov_b32_dpp v45, v33 row_ror:1 row_mask:0xf bank_mask:0xf
	v_cndmask_b32_e64 v41, v43, v37, s[12:13]
	v_pk_fma_f32 v[16:17], v[88:89], v[16:17], v[92:93]
	v_cndmask_b32_e64 v36, v44, v38, s[12:13]
	v_cndmask_b32_e64 v37, v48, v38, s[14:15]
	v_cndmask_b32_e64 v38, v49, v39, s[14:15]
	v_pk_fma_f32 v[16:17], v[80:81], v[40:41], v[16:17]
	v_cndmask_b32_e64 v18, v37, v18, s[12:13]
	v_cndmask_b32_e64 v37, v45, v39, s[12:13]
	v_cndmask_b32_e64 v19, v38, v19, s[12:13]
	v_pk_fma_f32 v[38:39], v[34:35], v[84:85], v[16:17]
	v_mov_b32_e32 v16, v161
	v_pk_fma_f32 v[18:19], v[90:91], v[18:19], v[94:95]
	v_mov_b32_dpp v50, v28 row_ror:1 row_mask:0xf bank_mask:0xf
	v_pk_fma_f32 v[18:19], v[82:83], v[36:37], v[18:19]
	v_lshlrev_b32_e32 v16, 2, v16
	v_pk_fma_f32 v[36:37], v[32:33], v[86:87], v[18:19]
	v_add_u32_e32 v32, v142, v16
	v_add_u32_e32 v16, s62, v16
	ds_read2_b32 v[40:41], v16 offset0:62 offset1:63
	ds_read_b128 v[16:19], v32 offset:144
	ds_read_b128 v[32:35], v32 offset:400
	v_mov_b32_dpp v54, v28 row_ror:2 row_mask:0xf bank_mask:0xf
	v_mov_b32_dpp v55, v29 row_ror:2 row_mask:0xf bank_mask:0xf
	s_waitcnt lgkmcnt(0)
	v_pk_mul_f32 v[32:33], v[32:33], v[40:41] op_sel:[0,1]
	v_mov_b32_dpp v51, v29 row_ror:1 row_mask:0xf bank_mask:0xf
	v_mov_b32_dpp v52, v30 row_ror:1 row_mask:0xf bank_mask:0xf
	v_mov_b32_dpp v56, v30 row_ror:2 row_mask:0xf bank_mask:0xf
	v_mov_b32_dpp v57, v31 row_ror:2 row_mask:0xf bank_mask:0xf
	v_pk_mul_f32 v[18:19], v[18:19], v[40:41] op_sel_hi:[1,0]
	v_pk_mul_f32 v[16:17], v[16:17], v[40:41] op_sel_hi:[1,0]
	v_pk_mul_f32 v[34:35], v[34:35], v[40:41] op_sel:[0,1]
	v_cndmask_b32_e64 v40, v50, v32, s[12:13]
	v_cndmask_b32_e64 v32, v54, v32, s[14:15]
	v_cndmask_b32_e64 v16, v32, v16, s[12:13]
	v_cndmask_b32_e64 v32, v55, v33, s[14:15]
	v_cndmask_b32_e64 v41, v51, v33, s[12:13]
	v_cndmask_b32_e64 v17, v32, v17, s[12:13]
	v_cndmask_b32_e64 v32, v52, v34, s[12:13]
	v_cndmask_b32_e64 v33, v56, v34, s[14:15]
	v_cndmask_b32_e64 v34, v57, v35, s[14:15]
	v_cndmask_b32_e64 v19, v34, v19, s[12:13]
	v_mul_f32_e32 v34, 0xbfb8aa3b, v38
	v_mov_b32_dpp v53, v31 row_ror:1 row_mask:0xf bank_mask:0xf
	v_exp_f32_e32 v34, v34
	v_cndmask_b32_e64 v18, v33, v18, s[12:13]
	v_cndmask_b32_e64 v33, v53, v35, s[12:13]
	v_pk_fma_f32 v[18:19], v[74:75], v[18:19], v[78:79]
	v_pk_fma_f32 v[16:17], v[72:73], v[16:17], v[76:77]
	v_pk_fma_f32 v[18:19], v[70:71], v[32:33], v[18:19]
	v_pk_fma_f32 v[16:17], v[68:69], v[40:41], v[16:17]
	v_pk_fma_f32 v[18:19], v[30:31], v[66:67], v[18:19]
	v_add_f32_e32 v30, 1.0, v34
	v_rcp_f32_e32 v30, v30
	v_mul_f32_e32 v31, 0xbfb8aa3b, v39
	v_exp_f32_e32 v31, v31
	v_pk_fma_f32 v[16:17], v[28:29], v[64:65], v[16:17]
	v_mul_f32_e32 v29, 0xbfb8aa3b, v36
	v_mul_f32_e32 v28, v38, v30
	v_exp_f32_e32 v29, v29
	v_mul_f32_e32 v30, 0xbfb8aa3b, v37
	v_exp_f32_e32 v30, v30
	v_mul_f32_e32 v16, v28, v16
	v_add_f32_e32 v28, 1.0, v31
	v_rcp_f32_e32 v28, v28
	v_add_f32_e32 v29, 1.0, v29
	v_rcp_f32_e32 v29, v29
	v_add_f32_e32 v30, 1.0, v30
	v_rcp_f32_e32 v30, v30
	v_mul_f32_e32 v28, v39, v28
	v_mul_f32_e32 v17, v28, v17
	v_mul_f32_e32 v28, v36, v29
	v_mul_f32_e32 v18, v28, v18
	v_mul_f32_e32 v28, v37, v30
	v_mul_f32_e32 v19, v28, v19
	v_cvt_pk_bf16_f32 v16, v16, v17
	v_cvt_pk_bf16_f32 v17, v18, v19
	global_store_dwordx2 v[110:111], v[16:17], off offset:8
	v_mov_b32_dpp v36, v24 row_ror:2 row_mask:0xf bank_mask:0xf
	v_mov_b32_dpp v37, v25 row_ror:2 row_mask:0xf bank_mask:0xf
	v_mov_b32_dpp v32, v24 row_ror:1 row_mask:0xf bank_mask:0xf
	v_mov_b32_dpp v33, v25 row_ror:1 row_mask:0xf bank_mask:0xf
	v_mov_b32_dpp v38, v26 row_ror:2 row_mask:0xf bank_mask:0xf
	v_mov_b32_dpp v39, v27 row_ror:2 row_mask:0xf bank_mask:0xf
	v_cndmask_b32_e64 v18, v36, v46, s[10:11]
	v_cndmask_b32_e64 v19, v37, v47, s[10:11]
	v_mov_b32_dpp v34, v26 row_ror:1 row_mask:0xf bank_mask:0xf
	v_mov_b32_dpp v35, v27 row_ror:1 row_mask:0xf bank_mask:0xf
	v_cndmask_b32_e64 v30, v32, v42, s[12:13]
	v_cndmask_b32_e64 v31, v33, v43, s[12:13]
	v_pk_fma_f32 v[18:19], v[88:89], v[18:19], v[92:93]
	v_mov_b32_dpp v46, v20 row_ror:2 row_mask:0xf bank_mask:0xf
	v_mov_b32_dpp v47, v21 row_ror:2 row_mask:0xf bank_mask:0xf
	v_cndmask_b32_e64 v17, v39, v49, s[10:11]
	v_cndmask_b32_e64 v16, v38, v48, s[10:11]
	v_pk_fma_f32 v[18:19], v[80:81], v[30:31], v[18:19]
	v_mov_b32_dpp v42, v20 row_ror:1 row_mask:0xf bank_mask:0xf
	v_mov_b32_dpp v43, v21 row_ror:1 row_mask:0xf bank_mask:0xf
	v_cndmask_b32_e64 v29, v35, v45, s[12:13]
	v_cndmask_b32_e64 v28, v34, v44, s[12:13]
	v_pk_fma_f32 v[16:17], v[90:91], v[16:17], v[94:95]
	v_pk_fma_f32 v[18:19], v[24:25], v[84:85], v[18:19]
	v_cndmask_b32_e64 v25, v47, v57, s[10:11]
	v_cndmask_b32_e64 v24, v46, v56, s[10:11]
	v_pk_fma_f32 v[16:17], v[82:83], v[28:29], v[16:17]
	v_cndmask_b32_e64 v29, v43, v53, s[12:13]
	v_cndmask_b32_e64 v28, v42, v52, s[12:13]
	v_pk_fma_f32 v[24:25], v[74:75], v[24:25], v[78:79]
	v_mov_b32_dpp v44, v22 row_ror:2 row_mask:0xf bank_mask:0xf
; #define LAS __attribute__((address_space(3)))
; __device__ __forceinline__ unsigned cvt_pk_bf16(float lo, float hi) { unsigned r; asm volatile("v_cvt_pk_bf16_f32 %0, %1, %2" : "=v"(r) : "v"(lo), "v"(hi)); return r; }
; __device__ __forceinline__ float sigm(float x) { return __builtin_amdgcn_rcpf(1.0f + __expf(-x)); }
; __device__ __forceinline__ int opq(int v) { asm volatile("" : "+v"(v)); return v; }
;     __device__ __forceinline__ void operator()(f32x4 (&acc)[2][2][4][2], const Unit& u, int wr, int wc, int fr, int fq) const {
;     ...
;                         const f32x4 cur = acc[ai][bj][m][n]; f32x4 p1 = ror4(cur, 1), p2 = ror4(cur, 2);
;                         if (m > 0) { const f32x4 pv = acc[ai][bj][m - 1][n]; const f32x4 q1 = ror4(pv, 1), q2 = ror4(pv, 2);
; #pragma unroll
;                             for (int e = 0; e < 4; ++e) { p1[e] = (fr == 0) ? q1[e] : p1[e]; p2[e] = (fr < 2) ? q2[e] : p2[e]; } }
;                         else { f32x4 h14 = (f32x4){0.f, 0.f, 0.f, 0.f}, h15 = h14;
;                             if (!(wr == 0 && ai == 0)) { const int sai = (wr == 1) ? ai : 0, swr = (wr == 1) ? 0 : 1; const int ox = opq(0);
;                                 const LAS float* hp = hl + (((((sai * 2 + swr) * 4 + wc) * 2 + 0) * 2 + bj) * 32 + 8 * fq + 4 * n) + ox;
;                                 const float r14 = rsL[sai * 128 + swr * 64 + 62 + ox], r15 = rsL[sai * 128 + swr * 64 + 63 + ox];
;                                 h14 = *(const LAS f32x4*)hp * r14; h15 = *(const LAS f32x4*)(hp + 64) * r15; }
; #pragma unroll
;                             for (int e = 0; e < 4; ++e) { p1[e] = (fr == 0) ? h15[e] : p1[e]; p2[e] = (fr == 0) ? h14[e] : ((fr == 1) ? h15[e] : p2[e]); } }
;                         const f32x4 w0 = bj ? wv0 : wg0, w1 = bj ? wv1 : wg1, w2 = bj ? wv2 : wg2, bb = bj ? bv : bg;
;                         gv[bj] = bb + w0 * p2 + w1 * p1 + w2 * cur;
;                     }
;                     float o[4];
; #pragma unroll
;                     for (int e = 0; e < 4; ++e) o[e] = gv[0][e] * sigm(gv[0][e]) * gv[1][e];
;                     u32x2 w; w.x = cvt_pk_bf16(o[0], o[1]); w.y = cvt_pk_bf16(o[2], o[3]);
;                     const bool edge = (wr == 0 && ai == 0 && m == 0 && fr < 2 && !seq0);
;                     if (!edge) *(u32x2*)(act + (size_t)(row0 + ai * 128 + m * 16) * DFF + colg0 + 4 * n) = w;
	v_pk_fma_f32 v[24:25], v[70:71], v[28:29], v[24:25]
	v_mov_b32_dpp v45, v23 row_ror:2 row_mask:0xf bank_mask:0xf
	v_pk_fma_f32 v[20:21], v[20:21], v[66:67], v[24:25]
	v_mul_f32_e32 v24, 0xbfb8aa3b, v18
	v_exp_f32_e32 v24, v24
	v_mov_b32_dpp v40, v22 row_ror:1 row_mask:0xf bank_mask:0xf
	v_mov_b32_dpp v41, v23 row_ror:1 row_mask:0xf bank_mask:0xf
	v_add_f32_e32 v24, 1.0, v24
	v_rcp_f32_e32 v24, v24
	v_pk_fma_f32 v[16:17], v[26:27], v[86:87], v[16:17]
	v_cndmask_b32_e64 v26, v44, v54, s[10:11]
	v_cndmask_b32_e64 v27, v45, v55, s[10:11]
	v_cndmask_b32_e64 v30, v40, v50, s[12:13]
	v_cndmask_b32_e64 v31, v41, v51, s[12:13]
	v_pk_fma_f32 v[26:27], v[72:73], v[26:27], v[76:77]
	v_mul_f32_e32 v18, v18, v24
	v_pk_fma_f32 v[26:27], v[68:69], v[30:31], v[26:27]
	s_nop 0
	v_pk_fma_f32 v[22:23], v[22:23], v[64:65], v[26:27]
	s_nop 0
	v_mul_f32_e32 v18, v18, v22
	v_mul_f32_e32 v22, 0xbfb8aa3b, v19
	v_exp_f32_e32 v22, v22
	s_nop 0
	v_add_f32_e32 v22, 1.0, v22
	v_rcp_f32_e32 v22, v22
	s_nop 0
	v_mul_f32_e32 v19, v19, v22
	v_mul_f32_e32 v22, 0xbfb8aa3b, v16
	v_exp_f32_e32 v22, v22
	v_mul_f32_e32 v19, v19, v23
	v_add_f32_e32 v22, 1.0, v22
	v_rcp_f32_e32 v22, v22
	s_nop 0
	v_mul_f32_e32 v16, v16, v22
	v_mul_f32_e32 v20, v16, v20
	v_mul_f32_e32 v16, 0xbfb8aa3b, v17
	v_exp_f32_e32 v16, v16
	s_nop 0
	v_add_f32_e32 v16, 1.0, v16
	v_rcp_f32_e32 v16, v16
	s_nop 0
	v_mul_f32_e32 v16, v17, v16
	v_mul_f32_e32 v17, v16, v21
	v_cvt_pk_bf16_f32 v16, v18, v19
	v_cvt_pk_bf16_f32 v17, v20, v17
	global_store_dwordx2 v[112:113], v[16:17], off offset:8
	v_mov_b32_dpp v30, v12 row_ror:2 row_mask:0xf bank_mask:0xf
	v_mov_b32_dpp v31, v13 row_ror:2 row_mask:0xf bank_mask:0xf
	v_mov_b32_dpp v26, v12 row_ror:1 row_mask:0xf bank_mask:0xf
	v_mov_b32_dpp v27, v13 row_ror:1 row_mask:0xf bank_mask:0xf
	v_mov_b32_dpp v28, v14 row_ror:2 row_mask:0xf bank_mask:0xf
	v_mov_b32_dpp v29, v15 row_ror:2 row_mask:0xf bank_mask:0xf
	v_cndmask_b32_e64 v17, v31, v39, s[10:11]
	v_cndmask_b32_e64 v16, v30, v38, s[10:11]
	v_mov_b32_dpp v24, v14 row_ror:1 row_mask:0xf bank_mask:0xf
	v_mov_b32_dpp v25, v15 row_ror:1 row_mask:0xf bank_mask:0xf
	v_cndmask_b32_e64 v21, v27, v35, s[12:13]
	v_cndmask_b32_e64 v20, v26, v34, s[12:13]
	v_pk_fma_f32 v[16:17], v[90:91], v[16:17], v[94:95]
	v_mov_b32_dpp v38, v10 row_ror:2 row_mask:0xf bank_mask:0xf
	v_mov_b32_dpp v39, v11 row_ror:2 row_mask:0xf bank_mask:0xf
	v_cndmask_b32_e64 v18, v28, v36, s[10:11]
	v_cndmask_b32_e64 v19, v29, v37, s[10:11]
	v_pk_fma_f32 v[16:17], v[82:83], v[20:21], v[16:17]
	v_mov_b32_dpp v34, v10 row_ror:1 row_mask:0xf bank_mask:0xf
	v_mov_b32_dpp v35, v11 row_ror:1 row_mask:0xf bank_mask:0xf
	v_cndmask_b32_e64 v22, v24, v32, s[12:13]
	v_cndmask_b32_e64 v23, v25, v33, s[12:13]
	v_pk_fma_f32 v[18:19], v[88:89], v[18:19], v[92:93]
	v_pk_fma_f32 v[12:13], v[12:13], v[86:87], v[16:17]
	v_cndmask_b32_e64 v17, v39, v47, s[10:11]
	v_cndmask_b32_e64 v16, v38, v46, s[10:11]
	v_pk_fma_f32 v[18:19], v[80:81], v[22:23], v[18:19]
	v_cndmask_b32_e64 v21, v35, v43, s[12:13]
	v_cndmask_b32_e64 v20, v34, v42, s[12:13]
	v_pk_fma_f32 v[16:17], v[74:75], v[16:17], v[78:79]
	v_pk_fma_f32 v[14:15], v[14:15], v[84:85], v[18:19]
	v_pk_fma_f32 v[16:17], v[70:71], v[20:21], v[16:17]
	v_mov_b32_dpp v36, v8 row_ror:2 row_mask:0xf bank_mask:0xf
	v_pk_fma_f32 v[10:11], v[10:11], v[66:67], v[16:17]
	v_mul_f32_e32 v16, 0xbfb8aa3b, v14
	v_exp_f32_e32 v16, v16
	v_mov_b32_dpp v37, v9 row_ror:2 row_mask:0xf bank_mask:0xf
	v_mov_b32_dpp v32, v8 row_ror:1 row_mask:0xf bank_mask:0xf
	v_mov_b32_dpp v33, v9 row_ror:1 row_mask:0xf bank_mask:0xf
	v_add_f32_e32 v16, 1.0, v16
	v_rcp_f32_e32 v16, v16
	v_cndmask_b32_e64 v18, v36, v44, s[10:11]
	v_cndmask_b32_e64 v19, v37, v45, s[10:11]
	v_cndmask_b32_e64 v22, v32, v40, s[12:13]
	v_cndmask_b32_e64 v23, v33, v41, s[12:13]
	v_pk_fma_f32 v[18:19], v[72:73], v[18:19], v[76:77]
	v_mul_f32_e32 v14, v14, v16
	v_pk_fma_f32 v[18:19], v[68:69], v[22:23], v[18:19]
	s_nop 0
; __device__ __forceinline__ unsigned cvt_pk_bf16(float lo, float hi) { unsigned r; asm volatile("v_cvt_pk_bf16_f32 %0, %1, %2" : "=v"(r) : "v"(lo), "v"(hi)); return r; }
; __device__ __forceinline__ float sigm(float x) { return __builtin_amdgcn_rcpf(1.0f + __expf(-x)); }
; #define PG8_BAR __builtin_amdgcn_s_barrier()
; template <class Epi>
; __device__ __forceinline__ void gemm_phase(LAS unsigned char* lds, const Gemm g, const StaticOrder& S, const Epi& E) {
;     ...
;         cur = nxt; cA = nA; cB = nB; ++ui;
;         if (wr == 1) PG8_BAR;
;     __device__ __forceinline__ void operator()(f32x4 (&acc)[2][2][4][2], const Unit& u, int wr, int wc, int fr, int fq) const {
;     ...
;                         const f32x4 w0 = bj ? wv0 : wg0, w1 = bj ? wv1 : wg1, w2 = bj ? wv2 : wg2, bb = bj ? bv : bg;
;                         gv[bj] = bb + w0 * p2 + w1 * p1 + w2 * cur;
;                     }
;                     float o[4];
; #pragma unroll
;                     for (int e = 0; e < 4; ++e) o[e] = gv[0][e] * sigm(gv[0][e]) * gv[1][e];
;                     u32x2 w; w.x = cvt_pk_bf16(o[0], o[1]); w.y = cvt_pk_bf16(o[2], o[3]);
;                     const bool edge = (wr == 0 && ai == 0 && m == 0 && fr < 2 && !seq0);
;                     if (!edge) *(u32x2*)(act + (size_t)(row0 + ai * 128 + m * 16) * DFF + colg0 + 4 * n) = w;
	v_pk_fma_f32 v[8:9], v[8:9], v[64:65], v[18:19]
	s_nop 0
	v_mul_f32_e32 v8, v14, v8
	v_mul_f32_e32 v14, 0xbfb8aa3b, v15
	v_exp_f32_e32 v14, v14
	s_nop 0
	v_add_f32_e32 v14, 1.0, v14
	v_rcp_f32_e32 v14, v14
	s_nop 0
	v_mul_f32_e32 v14, v15, v14
	v_mul_f32_e32 v9, v14, v9
	v_mul_f32_e32 v14, 0xbfb8aa3b, v12
	v_exp_f32_e32 v14, v14
	v_cvt_pk_bf16_f32 v8, v8, v9
	s_nop 0
	v_add_f32_e32 v14, 1.0, v14
	v_rcp_f32_e32 v14, v14
	s_nop 0
	v_mul_f32_e32 v12, v12, v14
	v_mul_f32_e32 v10, v12, v10
	v_mul_f32_e32 v12, 0xbfb8aa3b, v13
	v_exp_f32_e32 v12, v12
	s_nop 0
	v_add_f32_e32 v12, 1.0, v12
	v_rcp_f32_e32 v12, v12
	s_nop 0
	v_mul_f32_e32 v12, v13, v12
	v_mul_f32_e32 v11, v12, v11
	v_cvt_pk_bf16_f32 v9, v10, v11
	global_store_dwordx2 v[114:115], v[8:9], off offset:8
	v_mov_b32_dpp v8, v4 row_ror:2 row_mask:0xf bank_mask:0xf
	v_mov_b32_dpp v14, v6 row_ror:2 row_mask:0xf bank_mask:0xf
	v_mov_b32_dpp v9, v7 row_ror:2 row_mask:0xf bank_mask:0xf
	v_mov_b32_dpp v12, v4 row_ror:1 row_mask:0xf bank_mask:0xf
	v_mov_b32_dpp v16, v6 row_ror:1 row_mask:0xf bank_mask:0xf
	v_mov_b32_dpp v13, v7 row_ror:1 row_mask:0xf bank_mask:0xf
	v_mov_b32_dpp v11, v5 row_ror:2 row_mask:0xf bank_mask:0xf
	v_mov_b32_dpp v15, v5 row_ror:1 row_mask:0xf bank_mask:0xf
	v_cndmask_b32_e64 v9, v9, v31, s[10:11]
	v_cndmask_b32_e64 v10, v8, v28, s[10:11]
	v_cndmask_b32_e64 v8, v14, v30, s[10:11]
	v_cndmask_b32_e64 v11, v11, v29, s[10:11]
	v_cndmask_b32_e64 v13, v13, v27, s[12:13]
	v_cndmask_b32_e64 v14, v12, v24, s[12:13]
	v_cndmask_b32_e64 v12, v16, v26, s[12:13]
	v_pk_fma_f32 v[8:9], v[90:91], v[8:9], v[94:95]
	v_cndmask_b32_e64 v15, v15, v25, s[12:13]
	v_pk_fma_f32 v[10:11], v[88:89], v[10:11], v[92:93]
	v_pk_fma_f32 v[8:9], v[82:83], v[12:13], v[8:9]
	v_pk_fma_f32 v[10:11], v[80:81], v[14:15], v[10:11]
	v_pk_fma_f32 v[6:7], v[6:7], v[86:87], v[8:9]
	v_mov_b32_dpp v12, v0 row_ror:1 row_mask:0xf bank_mask:0xf
	v_mov_b32_dpp v16, v2 row_ror:1 row_mask:0xf bank_mask:0xf
	v_mov_b32_dpp v8, v0 row_ror:2 row_mask:0xf bank_mask:0xf
	v_mov_b32_dpp v14, v2 row_ror:2 row_mask:0xf bank_mask:0xf
	v_pk_fma_f32 v[4:5], v[4:5], v[84:85], v[10:11]
	v_mov_b32_dpp v9, v3 row_ror:2 row_mask:0xf bank_mask:0xf
	v_cndmask_b32_e64 v10, v8, v36, s[10:11]
	v_cndmask_b32_e64 v8, v14, v38, s[10:11]
	v_cndmask_b32_e64 v14, v12, v32, s[12:13]
	v_cndmask_b32_e64 v12, v16, v34, s[12:13]
	v_mul_f32_e32 v16, 0xbfb8aa3b, v4
	v_mov_b32_dpp v13, v3 row_ror:1 row_mask:0xf bank_mask:0xf
	v_exp_f32_e32 v16, v16
	v_cndmask_b32_e64 v9, v9, v39, s[10:11]
	v_cndmask_b32_e64 v13, v13, v35, s[12:13]
	v_pk_fma_f32 v[8:9], v[74:75], v[8:9], v[78:79]
	v_mov_b32_dpp v11, v1 row_ror:2 row_mask:0xf bank_mask:0xf
	v_pk_fma_f32 v[8:9], v[70:71], v[12:13], v[8:9]
	v_mov_b32_dpp v15, v1 row_ror:1 row_mask:0xf bank_mask:0xf
	v_pk_fma_f32 v[2:3], v[2:3], v[66:67], v[8:9]
	v_add_f32_e32 v8, 1.0, v16
	v_rcp_f32_e32 v8, v8
	v_mul_f32_e32 v9, 0xbfb8aa3b, v5
	v_cndmask_b32_e64 v11, v11, v37, s[10:11]
	v_exp_f32_e32 v9, v9
	v_cndmask_b32_e64 v15, v15, v33, s[12:13]
	v_pk_fma_f32 v[10:11], v[72:73], v[10:11], v[76:77]
	v_mul_f32_e32 v4, v4, v8
	v_pk_fma_f32 v[10:11], v[68:69], v[14:15], v[10:11]
	v_mul_f32_e32 v8, 0xbfb8aa3b, v6
	v_pk_fma_f32 v[0:1], v[0:1], v[64:65], v[10:11]
	v_exp_f32_e32 v8, v8
	v_mul_f32_e32 v0, v4, v0
	v_add_f32_e32 v4, 1.0, v9
	v_rcp_f32_e32 v4, v4
	v_mul_f32_e32 v9, 0xbfb8aa3b, v7
	v_exp_f32_e32 v9, v9
	v_mul_f32_e32 v4, v5, v4
	v_add_f32_e32 v5, 1.0, v8
	v_rcp_f32_e32 v5, v5
	v_add_f32_e32 v8, 1.0, v9
	v_rcp_f32_e32 v8, v8
	v_mul_f32_e32 v1, v4, v1
	v_mul_f32_e32 v4, v6, v5
	v_mul_f32_e32 v2, v4, v2
	v_mul_f32_e32 v4, v7, v8
	v_mul_f32_e32 v3, v4, v3
	v_cvt_pk_bf16_f32 v0, v0, v1
	v_cvt_pk_bf16_f32 v1, v2, v3
	global_store_dwordx2 v[96:97], v[0:1], off offset:8
	s_andn2_b64 vcc, exec, s[8:9]
	s_mov_b64 s[8:9], -1
	s_cbranch_vccnz .LBB0_1023
	s_mov_b32 s32, 0
	s_andn2_b64 vcc, exec, s[42:43]
	s_cbranch_vccnz .LBB0_1022
	s_mov_b32 s32, 1
	s_branch .LBB0_1022
